# v19 + MLA loop: K address offset folded into base once per job, redundant max canonicalisation and zero-init packed adds removed
# baseline (speedup 1.0000x reference)
; DI int get_tid() { int t = threadIdx.x; asm volatile("" : "+v"(t)); return t; }
; template <int DK, int MODE> ...
;     ...
;   const int tid = get_tid(), lane = tid & 63, wave = __builtin_amdgcn_readfirstlane(tid >> 6), l32 = lane & 31, h = lane >> 5;
;   const int tq0 = qb * 128 + 32 * wave;
;   const int qpos = tq0 + l32;
;   bf16x8 qf[NKS];
;   {
;     const bf16_t* qp = Q + (size_t)qpos * DK + h * 8;
; #pragma unroll
;     for (int ks = 0; ks < NKS; ++ks) qf[ks] = *(const bf16x8*)(qp + ks * 16);
; #pragma unroll
;     for (int ks = 0; ks < NKS; ++ks) asm volatile("" : "+v"(qf[ks]));
;   }
;   float Fref = 0.f;
;   if (MODE == 1) Fref = F[qb * 128];
;   f32x16 o0, o1;
; #pragma unroll
;   for (int e = 0; e < 16; ++e) { o0[e] = 0.f; o1[e] = 0.f; }
;   float m = -1e30f, lsum = 0.f, R = 1.f;
;     ...
;   gload(ASC ? start : ntiles - 1);
;   swrite(0);
;   __syncthreads();
.LBB0_522:
	s_and_b64 s[0:1], s[56:57], exec
	s_cselect_b32 s0, s63, s64
	s_and_b64 vcc, exec, s[48:49]
	s_mov_b64 s[4:5], -1
	s_cbranch_vccz .LBB0_541
	s_load_dwordx2 s[20:21], s[18:19], 0x110
	s_load_dwordx4 s[8:11], s[18:19], 0x100
	v_mov_b32_e32 v36, v188
	s_load_dwordx4 s[4:7], s[18:19], 0x90
	v_mov_b32_e32 v161, v1
	s_waitcnt lgkmcnt(0)
	s_add_u32 s12, s8, s52
	s_addc_u32 s13, s9, s53
	s_add_u32 s22, s10, s52
	s_addc_u32 s23, s11, s53
	s_add_u32 s8, s20, s50
	v_readfirstlane_b32 s1, v36
	s_addc_u32 s9, s21, s51
	s_ashr_i32 s1, s1, 1
	s_lshl_b32 s2, s0, 7
	s_andn2_b32 s1, s1, 31
	v_and_b32_e32 v37, 31, v36
	s_add_i32 s1, s1, s2
	v_bfe_u32 v38, v36, 5, 1
	v_or_b32_e32 v152, s1, v37
	s_waitcnt vmcnt(7)
	v_mov_b64_e32 v[2:3], s[12:13]
	v_mad_i64_i32 v[2:3], s[12:13], v152, s78, v[2:3]
	v_lshlrev_b32_e32 v0, 4, v38
	v_lshl_add_u64 v[2:3], v[2:3], 0, v[0:1]
	global_load_dwordx4 v[80:83], v[2:3], off
	global_load_dwordx4 v[128:131], v[2:3], off offset:32
	global_load_dwordx4 v[124:127], v[2:3], off offset:64
	global_load_dwordx4 v[120:123], v[2:3], off offset:96
	global_load_dwordx4 v[116:119], v[2:3], off offset:128
	global_load_dwordx4 v[112:115], v[2:3], off offset:160
	v_mul_hi_i32 v2, v36, s69
	v_lshrrev_b32_e32 v3, 31, v2
	v_ashrrev_i32_e32 v2, 1, v2
	s_waitcnt vmcnt(7)
	v_add_u32_e32 v28, 0x100, v36
	v_add_u32_e32 v39, v2, v3
	v_mul_hi_i32 v6, v28, s69
	v_mul_lo_u32 v2, v39, 12
	v_lshrrev_b32_e32 v7, 31, v6
	v_ashrrev_i32_e32 v6, 1, v6
	v_add_u32_e32 v12, 0x200, v36
	v_sub_u32_e32 v40, v36, v2
	v_add_u32_e32 v41, v6, v7
	v_mul_hi_i32 v13, v12, s69
	v_lshlrev_b32_e32 v154, 3, v40
	v_mul_lo_u32 v6, v41, 12
	v_lshrrev_b32_e32 v18, 31, v13
	v_ashrrev_i32_e32 v13, 1, v13
	v_mov_b64_e32 v[10:11], s[22:23]
	v_ashrrev_i32_e32 v155, 31, v154
	v_sub_u32_e32 v42, v28, v6
	v_add_u32_e32 v43, v13, v18
	v_mad_i64_i32 v[2:3], s[12:13], v39, s78, v[10:11]
	v_lshlrev_b64 v[14:15], 1, v[154:155]
	v_lshlrev_b32_e32 v156, 3, v42
	v_mul_lo_u32 v13, v43, 12
	v_lshl_add_u64 v[2:3], v[2:3], 0, v[14:15]
	v_ashrrev_i32_e32 v157, 31, v156
	v_sub_u32_e32 v44, v12, v13
	v_ashrrev_i32_e32 v22, 3, v36
	v_mad_i64_i32 v[6:7], s[12:13], v41, s78, v[10:11]
	v_lshlrev_b64 v[16:17], 1, v[156:157]
	v_lshlrev_b32_e32 v158, 3, v44
	v_ashrrev_i32_e32 v23, 31, v22
	v_lshl_add_u64 v[6:7], v[6:7], 0, v[16:17]
	v_ashrrev_i32_e32 v159, 31, v158
	v_lshlrev_b64 v[20:21], 14, v[22:23]
	v_lshlrev_b32_e32 v23, 3, v36
	s_waitcnt vmcnt(6)
	v_ashrrev_i32_e32 v32, 3, v28
	v_mad_i64_i32 v[10:11], s[12:13], v43, s78, v[10:11]
	v_lshlrev_b64 v[18:19], 1, v[158:159]
	v_and_b32_e32 v23, 56, v23
	v_ashrrev_i32_e32 v33, 31, v32
	v_lshl_add_u64 v[10:11], v[10:11], 0, v[18:19]
	v_lshl_add_u64 v[24:25], s[8:9], 0, v[20:21]
	v_lshlrev_b32_e32 v160, 1, v23
	v_lshlrev_b64 v[34:35], 14, v[32:33]
	v_lshl_add_u64 v[24:25], v[24:25], 0, v[160:161]
	v_lshl_add_u64 v[28:29], s[8:9], 0, v[34:35]
	v_lshl_add_u64 v[28:29], v[28:29], 0, v[160:161]
	v_mul_lo_u32 v159, v39, s70
	v_lshlrev_b32_e32 v23, 4, v40
	v_lshl_add_u32 v23, v159, 1, v23
	v_mul_lo_u32 v161, v41, s70
	s_or_b32 s8, s1, 31
	s_movk_i32 s9, 0xd0
	s_or_b32 s2, s2, 64
	v_mad_u32_u24 v175, v37, s9, v0
	s_add_u32 s9, s20, s44
	v_mul_lo_u32 v172, v43, s70
	v_lshlrev_b32_e32 v0, 6, v37
	s_addc_u32 s13, s21, s45
	v_mul_lo_u32 v173, v22, s33
	v_sub_u32_e32 v157, v175, v0
	s_waitcnt vmcnt(5)
	s_waitcnt vmcnt(4)
	s_waitcnt vmcnt(3)
	s_waitcnt vmcnt(2)
	s_waitcnt vmcnt(1)
	s_waitcnt vmcnt(0)
	global_load_dwordx4 v[2:5], v[2:3], off
	s_add_u32 s12, s9, 0x80
	global_load_dwordx4 v[6:9], v[6:7], off
	v_lshlrev_b32_e32 v0, 4, v36
	global_load_dwordx4 v[10:13], v[10:11], off
	v_mul_lo_u32 v174, v32, s33
	global_load_dwordx4 v[24:27], v[24:25], off
	s_addc_u32 s13, s13, 0
	global_load_dwordx4 v[28:31], v[28:29], off
	v_and_b32_e32 v0, 0x70, v0
	v_or_b32_e32 v34, v34, v0
	v_or_b32_e32 v20, v20, v0
	s_add_u32 s10, s10, 0x3000
	v_lshl_add_u64 v[162:163], s[12:13], 0, v[34:35]
	v_lshl_add_u64 v[164:165], s[12:13], 0, v[20:21]
	s_addc_u32 s11, s11, 0
	v_lshlrev_b32_e32 v149, 2, v38
	v_mov_b32_e32 v0, v1
	v_ashrrev_i32_e32 v153, 31, v152
	s_mov_b32 s9, 0
	v_mov_b32_e32 v155, 0xf149f2ca
	v_mov_b32_e32 v151, 0
	s_waitcnt vmcnt(4)
	ds_write_b128 v23, v[2:5]
	v_lshlrev_b32_e32 v2, 4, v42
	v_lshl_add_u32 v2, v161, 1, v2
	s_waitcnt vmcnt(3)
	ds_write_b128 v2, v[6:9]
	v_lshlrev_b32_e32 v2, 4, v44
	v_lshl_add_u32 v2, v172, 1, v2
	s_waitcnt vmcnt(2)
	ds_write_b128 v2, v[10:13]
	v_lshl_add_u32 v2, v173, 1, v160
	s_waitcnt vmcnt(1)
	ds_write_b128 v2, v[24:27] offset:26624
	v_lshl_add_u32 v2, v174, 1, v160
	s_waitcnt vmcnt(0)
	ds_write_b128 v2, v[28:31] offset:26624
	v_mad_i64_i32 v[2:3], s[12:13], v43, s78, v[18:19]
	v_lshl_add_u64 v[166:167], s[10:11], 0, v[2:3]
	v_mad_i64_i32 v[2:3], s[12:13], v41, s78, v[16:17]
	v_lshl_add_u64 v[168:169], s[10:11], 0, v[2:3]
	v_mad_i64_i32 v[2:3], s[12:13], v39, s78, v[14:15]
	v_mov_b32_e32 v14, v1
	v_mov_b32_e32 v15, v1
	v_lshl_add_u64 v[170:171], s[10:11], 0, v[2:3]
	v_mov_b32_e32 v2, v1
	v_mov_b32_e32 v3, v1
	v_mov_b32_e32 v4, v1
	v_mov_b32_e32 v5, v1
	v_mov_b32_e32 v6, v1
	v_mov_b32_e32 v7, v1
	v_mov_b32_e32 v8, v1
	v_mov_b32_e32 v9, v1
	v_mov_b32_e32 v10, v1
	v_mov_b32_e32 v11, v1
	v_mov_b32_e32 v12, v1
	v_mov_b32_e32 v13, v1
	v_mov_b64_e32 v[30:31], v[14:15]
	v_mov_b64_e32 v[46:47], v[14:15]
	s_mov_b32 s10, 0
	v_mov_b64_e32 v[28:29], v[12:13]
	v_mov_b64_e32 v[26:27], v[10:11]
	v_mov_b64_e32 v[24:25], v[8:9]
	v_mov_b64_e32 v[22:23], v[6:7]
	v_mov_b64_e32 v[20:21], v[4:5]
	v_mov_b64_e32 v[18:19], v[2:3]
	v_mov_b64_e32 v[16:17], v[0:1]
	v_mov_b64_e32 v[44:45], v[12:13]
	v_mov_b64_e32 v[42:43], v[10:11]
	v_mov_b64_e32 v[40:41], v[8:9]
	v_mov_b64_e32 v[38:39], v[6:7]
	v_mov_b64_e32 v[36:37], v[4:5]
	v_mov_b64_e32 v[34:35], v[2:3]
	v_mov_b64_e32 v[32:33], v[0:1]
	s_waitcnt lgkmcnt(0)
	s_barrier
	v_lshlrev_b32_e32 v217, 1, v159
	v_lshl_add_u32 v217, v154, 1, v217
	v_lshlrev_b32_e32 v218, 1, v161
	v_lshl_add_u32 v218, v156, 1, v218
	v_lshlrev_b32_e32 v219, 1, v172
	v_lshl_add_u32 v219, v158, 1, v219
	v_lshl_add_u32 v220, v173, 1, v160
	v_lshl_add_u32 v221, v174, 1, v160
	v_lshl_add_u64 v[166:167], v[166:167], 0, s[46:47]
	v_lshl_add_u64 v[168:169], v[168:169], 0, s[46:47]
	v_lshl_add_u64 v[170:171], v[170:171], 0, s[46:47]
	s_branch .LBB0_526
; #define MFMA(a, b, c) __builtin_amdgcn_mfma_f32_32x32x16_bf16((a), (b), (c), 0, 0, 0)
; DI unsigned pack2(float a, float b) { f32x2 v = {a, b}; return __builtin_bit_cast(unsigned, __builtin_convertvector(v, bf16v2)); }
; template <int DK, int MODE> ...
;     ...
;         float ps0 = 0.f, ps1 = 0.f, ps2 = 0.f, ps3 = 0.f;
; #pragma unroll
;         for (int e = 0; e < 16; e += 4) {
;           s0[e] = __builtin_amdgcn_exp2f(s0[e] - m); s0[e + 1] = __builtin_amdgcn_exp2f(s0[e + 1] - m); s0[e + 2] = __builtin_amdgcn_exp2f(s0[e + 2] - m); s0[e + 3] = __builtin_amdgcn_exp2f(s0[e + 3] - m);
;           ps0 += s0[e]; ps1 += s0[e + 1]; ps2 += s0[e + 2]; ps3 += s0[e + 3];
;         }
; #pragma unroll
;         for (int e = 0; e < 16; e += 4) {
;           s1[e] = __builtin_amdgcn_exp2f(s1[e] - m); s1[e + 1] = __builtin_amdgcn_exp2f(s1[e + 1] - m); s1[e + 2] = __builtin_amdgcn_exp2f(s1[e + 2] - m); s1[e + 3] = __builtin_amdgcn_exp2f(s1[e + 3] - m);
;           ps0 += s1[e]; ps1 += s1[e + 1]; ps2 += s1[e + 2]; ps3 += s1[e + 3];
;         }
;         lsum += (ps0 + ps1) + (ps2 + ps3);
;     ...
; #pragma unroll
;       for (int j = 0; j < 2; ++j) {
;         u32x4 a, b;
;         a.x = pack2(s0[8 * j], s0[8 * j + 1]); a.y = pack2(s0[8 * j + 2], s0[8 * j + 3]); a.z = pack2(s0[8 * j + 4], s0[8 * j + 5]); a.w = pack2(s0[8 * j + 6], s0[8 * j + 7]);
;         b.x = pack2(s1[8 * j], s1[8 * j + 1]); b.y = pack2(s1[8 * j + 2], s1[8 * j + 3]); b.z = pack2(s1[8 * j + 4], s1[8 * j + 5]); b.w = pack2(s1[8 * j + 6], s1[8 * j + 7]);
;         pf[j] = __builtin_bit_cast(bf16x8, a); pf[2 + j] = __builtin_bit_cast(bf16x8, b);
;       }
;       __builtin_amdgcn_s_setprio(1);
; #pragma unroll
;       for (int j = 0; j < 4; ++j) { o0 = MFMA(vf0[j], pf[j], o0); o1 = MFMA(vf1[j], pf[j], o1); }
;       __builtin_amdgcn_s_setprio(0);
.LBB0_524:
	v_sub_f32_e32 v0, v64, v155
	v_exp_f32_e32 v14, v0
	v_sub_f32_e32 v0, v65, v155
	v_exp_f32_e32 v64, v0
	v_sub_f32_e32 v0, v66, v155
	v_exp_f32_e32 v15, v0
	v_sub_f32_e32 v0, v67, v155
	v_exp_f32_e32 v65, v0
	v_sub_f32_e32 v0, v68, v155
	v_exp_f32_e32 v66, v0
	v_sub_f32_e32 v0, v69, v155
	v_exp_f32_e32 v68, v0
	v_sub_f32_e32 v0, v70, v155
	v_exp_f32_e32 v67, v0
	v_sub_f32_e32 v0, v71, v155
	v_exp_f32_e32 v69, v0
	v_sub_f32_e32 v0, v72, v155
	v_exp_f32_e32 v70, v0
	v_sub_f32_e32 v0, v73, v155
	v_exp_f32_e32 v72, v0
	v_sub_f32_e32 v0, v74, v155
	v_exp_f32_e32 v71, v0
	v_sub_f32_e32 v0, v75, v155
	v_exp_f32_e32 v73, v0
	v_sub_f32_e32 v0, v76, v155
	v_exp_f32_e32 v74, v0
	v_sub_f32_e32 v0, v77, v155
	v_exp_f32_e32 v76, v0
	v_sub_f32_e32 v0, v78, v155
	v_exp_f32_e32 v75, v0
	v_sub_f32_e32 v0, v79, v155
	v_exp_f32_e32 v77, v0
	v_sub_f32_e32 v0, v48, v155
	v_exp_f32_e32 v78, v0
	v_sub_f32_e32 v0, v49, v155
	v_exp_f32_e32 v176, v0
	v_sub_f32_e32 v0, v50, v155
	v_exp_f32_e32 v79, v0
	v_sub_f32_e32 v0, v51, v155
	v_exp_f32_e32 v177, v0
	v_sub_f32_e32 v0, v52, v155
	v_exp_f32_e32 v178, v0
	v_sub_f32_e32 v0, v53, v155
	v_exp_f32_e32 v180, v0
	v_sub_f32_e32 v0, v54, v155
	v_exp_f32_e32 v179, v0
	v_sub_f32_e32 v0, v55, v155
	v_exp_f32_e32 v181, v0
	v_sub_f32_e32 v0, v56, v155
	v_exp_f32_e32 v182, v0
	v_sub_f32_e32 v0, v57, v155
	v_exp_f32_e32 v184, v0
	v_sub_f32_e32 v0, v58, v155
	v_exp_f32_e32 v183, v0
	v_sub_f32_e32 v0, v59, v155
	v_exp_f32_e32 v185, v0
	v_sub_f32_e32 v0, v60, v155
	v_exp_f32_e32 v186, v0
	v_sub_f32_e32 v0, v61, v155
	v_exp_f32_e32 v200, v0
	v_sub_f32_e32 v0, v62, v155
	v_pk_add_f32 v[48:49], v[66:67], v[14:15]
	v_pk_add_f32 v[50:51], v[68:69], v[64:65]
	v_exp_f32_e32 v187, v0
	v_sub_f32_e32 v0, v63, v155
	v_pk_add_f32 v[48:49], v[70:71], v[48:49]
	v_pk_add_f32 v[50:51], v[72:73], v[50:51]
	v_exp_f32_e32 v201, v0
	v_pk_add_f32 v[202:203], v[74:75], v[48:49]
	v_pk_add_f32 v[204:205], v[76:77], v[50:51]
	v_cvt_pk_bf16_f32 v48, v14, v64
	v_cvt_pk_bf16_f32 v49, v15, v65
	v_pk_add_f32 v[14:15], v[78:79], v[202:203]
	v_pk_add_f32 v[64:65], v[176:177], v[204:205]
	v_pk_add_f32 v[14:15], v[178:179], v[14:15]
	v_pk_add_f32 v[64:65], v[180:181], v[64:65]
	v_pk_add_f32 v[14:15], v[182:183], v[14:15]
	v_pk_add_f32 v[64:65], v[184:185], v[64:65]
	v_pk_add_f32 v[14:15], v[186:187], v[14:15]
	v_pk_add_f32 v[64:65], v[200:201], v[64:65]
	v_cvt_pk_bf16_f32 v50, v66, v68
	v_pk_add_f32 v[14:15], v[14:15], v[64:65]
	v_cvt_pk_bf16_f32 v51, v67, v69
	v_cvt_pk_bf16_f32 v52, v78, v176
	v_cvt_pk_bf16_f32 v53, v79, v177
	v_cvt_pk_bf16_f32 v54, v178, v180
	v_cvt_pk_bf16_f32 v55, v179, v181
	v_cvt_pk_bf16_f32 v56, v70, v72
	v_cvt_pk_bf16_f32 v57, v71, v73
	v_cvt_pk_bf16_f32 v58, v74, v76
	v_cvt_pk_bf16_f32 v59, v75, v77
	v_cvt_pk_bf16_f32 v60, v182, v184
	v_cvt_pk_bf16_f32 v61, v183, v185
	v_cvt_pk_bf16_f32 v62, v186, v200
	v_cvt_pk_bf16_f32 v63, v187, v201
	v_add_f32_e32 v0, v14, v15
	s_setprio 1
	v_mfma_f32_32x32x16_bf16 v[16:31], v[136:139], v[48:51], v[16:31]
	v_add_f32_e32 v151, v151, v0
	v_mfma_f32_32x32x16_bf16 v[32:47], v[140:143], v[48:51], v[32:47]
	v_mfma_f32_32x32x16_bf16 v[16:31], v[108:111], v[56:59], v[16:31]
	v_mfma_f32_32x32x16_bf16 v[32:47], v[132:135], v[56:59], v[32:47]
	v_mfma_f32_32x32x16_bf16 v[16:31], v[100:103], v[52:55], v[16:31]
	v_mfma_f32_32x32x16_bf16 v[32:47], v[104:107], v[52:55], v[32:47]
	v_mfma_f32_32x32x16_bf16 v[16:31], v[96:99], v[60:63], v[16:31]
	v_mfma_f32_32x32x16_bf16 v[32:47], v[92:95], v[60:63], v[32:47]
	s_setprio 0

; #define MFMA(a, b, c) __builtin_amdgcn_mfma_f32_32x32x16_bf16((a), (b), (c), 0, 0, 0)
; template <int DK, int MODE> ...
;     ...
;   auto gload = [&](int jt) {
; #pragma unroll
;     for (int i = 0; i < NKL; ++i) {
;       const int id = tid + 256 * i, row = id / KCH, ch = id % KCH;
;       rk[i] = *(const u32x4*)(K + (size_t)(jt * 64 + row) * DK + ch * 8);
;     }
; #pragma unroll
;     for (int i = 0; i < 2; ++i) {
;       const int id = tid + 256 * i, row = id >> 3, ch = id & 7;
;       rv[i] = *(const u32x4*)(Vt + (size_t)row * Skv + jt * 64 + ch * 8);
;     }
;     if (MODE == 1) rf = F[jt * 64 + (tid & 63)];
;   };
;     ...
;     if (more) gload(ASC ? jt + 1 : jt - 1);
;     const int key0 = jt * 64;
;     const bool active = !CAUSAL || (key0 <= tq0 + 31);
;     if (active) {
;       f32x16 s0, s1;
;       const bf16_t* kb = sK + cur * 64 * LDK + l32 * LDK + h * 8;
;       bf16x8 kf0[NKS], kf1[NKS];
; #pragma unroll
;       for (int ks = 0; ks < NKS; ++ks) { kf0[ks] = *(const bf16x8*)(kb + ks * 16); kf1[ks] = *(const bf16x8*)(kb + 32 * LDK + ks * 16); }
;       if (MODE == 1) {
;         const float* fb = sF + cur * 64 + 4 * h;
; #pragma unroll
;         for (int g = 0; g < 4; ++g) {
;           const f32x4 f0 = *(const f32x4*)(fb + 8 * g), f1 = *(const f32x4*)(fb + 32 + 8 * g);
;           s0[4 * g] = f0.x; s0[4 * g + 1] = f0.y; s0[4 * g + 2] = f0.z; s0[4 * g + 3] = f0.w;
;           s1[4 * g] = f1.x; s1[4 * g + 1] = f1.y; s1[4 * g + 2] = f1.z; s1[4 * g + 3] = f1.w;
;         }
;       } else {
; #pragma unroll
;         for (int e = 0; e < 16; ++e) { s0[e] = 0.f; s1[e] = 0.f; }
;       }
;       __builtin_amdgcn_iglp_opt(0);
;       __builtin_amdgcn_s_setprio(1);
; #pragma unroll
;       for (int ks = 0; ks < NKS; ++ks) { s0 = MFMA(kf0[ks], qf[ks], s0); s1 = MFMA(kf1[ks], qf[ks], s1); }
.LBB0_526:
	s_and_b32 s11, s10, 1
	s_cmp_gt_i32 s9, s8
	s_cbranch_scc1 .Lmla_inactive
	s_mul_i32 s12, s11, 0x3400
	v_add_u32_e32 v0, s12, v175
	ds_read_b128 v[48:51], v0 offset:6656
	ds_read_b128 v[52:55], v0
	ds_read_b128 v[92:95], v0 offset:32
	ds_read_b128 v[96:99], v0 offset:6688
	ds_read_b128 v[100:103], v0 offset:64
	ds_read_b128 v[104:107], v0 offset:6720
	ds_read_b128 v[108:111], v0 offset:96
	ds_read_b128 v[132:135], v0 offset:6752
	ds_read_b128 v[136:139], v0 offset:128
	ds_read_b128 v[140:143], v0 offset:6784
	ds_read_b128 v[176:179], v0 offset:160
	ds_read_b128 v[180:183], v0 offset:6816
	s_setprio 1
	s_setprio 0
	s_waitcnt lgkmcnt(10)
	v_mfma_f32_32x32x16_bf16 v[64:79], v[52:55], v[80:83], 0
	s_mul_i32 s12, s11, 0x2400
	v_add_u32_e32 v0, s12, v157
	v_mfma_f32_32x32x16_bf16 v[48:63], v[48:51], v[80:83], 0
	global_load_dwordx4 v[88:91], v[170:171], off
	s_waitcnt lgkmcnt(9)
	v_mfma_f32_32x32x16_bf16 v[64:79], v[92:95], v[128:131], v[64:79]
	ds_read_b128 v[92:95], v0 offset:31328
	s_waitcnt lgkmcnt(9)
	v_mfma_f32_32x32x16_bf16 v[48:63], v[96:99], v[128:131], v[48:63]
	global_load_dwordx4 v[84:87], v[168:169], off
	ds_read_b128 v[96:99], v0 offset:26720
	s_waitcnt lgkmcnt(9)
	v_mfma_f32_32x32x16_bf16 v[64:79], v[100:103], v[124:127], v[64:79]
	ds_read_b128 v[100:103], v0 offset:26688
	s_waitcnt lgkmcnt(9)
	v_mfma_f32_32x32x16_bf16 v[48:63], v[104:107], v[124:127], v[48:63]
	global_load_dwordx4 v[10:13], v[166:167], off
	ds_read_b128 v[104:107], v0 offset:31296
	s_waitcnt lgkmcnt(9)
	v_mfma_f32_32x32x16_bf16 v[64:79], v[108:111], v[120:123], v[64:79]
	ds_read_b128 v[108:111], v0 offset:26656
	s_waitcnt lgkmcnt(9)
	v_mfma_f32_32x32x16_bf16 v[48:63], v[132:135], v[120:123], v[48:63]
	global_load_dwordx4 v[6:9], v[164:165], off
	ds_read_b128 v[132:135], v0 offset:31264
	s_waitcnt lgkmcnt(9)
	v_mfma_f32_32x32x16_bf16 v[64:79], v[136:139], v[116:119], v[64:79]
	ds_read_b128 v[136:139], v0 offset:26624
	s_waitcnt lgkmcnt(9)
	v_mfma_f32_32x32x16_bf16 v[48:63], v[140:143], v[116:119], v[48:63]
	s_nop 0
	global_load_dwordx4 v[2:5], v[162:163], off
	ds_read_b128 v[140:143], v0 offset:31232
	s_waitcnt lgkmcnt(9)
	v_mfma_f32_32x32x16_bf16 v[64:79], v[176:179], v[112:115], v[64:79]
	s_waitcnt lgkmcnt(8)
	v_mfma_f32_32x32x16_bf16 v[48:63], v[180:183], v[112:115], v[48:63]
	s_add_i32 s12, s9, 63
	s_cmp_lt_i32 s12, s1
	s_cbranch_scc1 .LBB0_529
	v_add_u32_e32 v0, s9, v149
	v_add_u32_e32 v14, 32, v0
	v_cmp_le_i32_e32 vcc, v14, v152
	v_add_u32_e32 v14, 33, v0
	s_nop 4
	v_cndmask_b32_e32 v48, v198, v48, vcc
	v_cmp_lt_i32_e32 vcc, v0, v152
	s_nop 1
	v_cndmask_b32_e32 v65, v198, v65, vcc
	v_cmp_le_i32_e32 vcc, v0, v152
	s_nop 1
	v_cndmask_b32_e32 v64, v198, v64, vcc
	v_cmp_le_i32_e32 vcc, v14, v152
	v_add_u32_e32 v14, 2, v0
	s_nop 0
	v_cndmask_b32_e32 v49, v198, v49, vcc
	v_cmp_le_i32_e32 vcc, v14, v152
	v_add_u32_e32 v14, 34, v0
	s_nop 0
	v_cndmask_b32_e32 v66, v198, v66, vcc
	v_cmp_le_i32_e32 vcc, v14, v152
	v_add_u32_e32 v14, 3, v0
	s_nop 0
	v_cndmask_b32_e32 v50, v198, v50, vcc
	v_cmp_le_i32_e32 vcc, v14, v152
	v_add_u32_e32 v14, 35, v0
	s_nop 0
	v_cndmask_b32_e32 v67, v198, v67, vcc
	v_cmp_le_i32_e32 vcc, v14, v152
	v_add_u32_e32 v14, 8, v0
	s_nop 0
	v_cndmask_b32_e32 v51, v198, v51, vcc
	v_cmp_le_i32_e32 vcc, v14, v152
	v_add_u32_e32 v14, 40, v0
	s_nop 0
	v_cndmask_b32_e32 v68, v198, v68, vcc
	v_cmp_le_i32_e32 vcc, v14, v152
	v_add_u32_e32 v14, 9, v0
	s_nop 0
	v_cndmask_b32_e32 v52, v198, v52, vcc
	v_cmp_le_i32_e32 vcc, v14, v152
	v_add_u32_e32 v14, 41, v0
	s_nop 0
	v_cndmask_b32_e32 v69, v198, v69, vcc
	v_cmp_le_i32_e32 vcc, v14, v152
	v_add_u32_e32 v14, 10, v0
	s_nop 0
	v_cndmask_b32_e32 v53, v198, v53, vcc
	v_cmp_le_i32_e32 vcc, v14, v152
	v_add_u32_e32 v14, 42, v0
	s_nop 0
	v_cndmask_b32_e32 v70, v198, v70, vcc
	v_cmp_le_i32_e32 vcc, v14, v152
	v_add_u32_e32 v14, 11, v0
	s_nop 0
	v_cndmask_b32_e32 v54, v198, v54, vcc
	v_cmp_le_i32_e32 vcc, v14, v152
	v_add_u32_e32 v14, 43, v0
	s_nop 0
	v_cndmask_b32_e32 v71, v198, v71, vcc
	v_cmp_le_i32_e32 vcc, v14, v152
	v_add_u32_e32 v14, 16, v0
	s_nop 0
	v_cndmask_b32_e32 v55, v198, v55, vcc
	v_cmp_le_i32_e32 vcc, v14, v152
	v_add_u32_e32 v14, 48, v0
	s_nop 0
	v_cndmask_b32_e32 v72, v198, v72, vcc
	v_cmp_le_i32_e32 vcc, v14, v152
	v_add_u32_e32 v14, 17, v0
	s_nop 0
	v_cndmask_b32_e32 v56, v198, v56, vcc
	v_cmp_le_i32_e32 vcc, v14, v152
	v_add_u32_e32 v14, 49, v0
	s_nop 0
	v_cndmask_b32_e32 v73, v198, v73, vcc
	v_cmp_le_i32_e32 vcc, v14, v152
	v_add_u32_e32 v14, 18, v0
	s_nop 0
	v_cndmask_b32_e32 v57, v198, v57, vcc
	v_cmp_le_i32_e32 vcc, v14, v152
	v_add_u32_e32 v14, 50, v0
	s_nop 0
	v_cndmask_b32_e32 v74, v198, v74, vcc
	v_cmp_le_i32_e32 vcc, v14, v152
	v_add_u32_e32 v14, 19, v0
	s_nop 0
	v_cndmask_b32_e32 v58, v198, v58, vcc
	v_cmp_le_i32_e32 vcc, v14, v152
	v_add_u32_e32 v14, 51, v0
	s_nop 0
	v_cndmask_b32_e32 v75, v198, v75, vcc
	v_cmp_le_i32_e32 vcc, v14, v152
	v_add_u32_e32 v14, 24, v0
	s_nop 0
	v_cndmask_b32_e32 v59, v198, v59, vcc
	v_cmp_le_i32_e32 vcc, v14, v152
	v_add_u32_e32 v14, 56, v0
	s_nop 0
	v_cndmask_b32_e32 v76, v198, v76, vcc
	v_cmp_le_i32_e32 vcc, v14, v152
	v_add_u32_e32 v14, 25, v0
	s_nop 0
	v_cndmask_b32_e32 v60, v198, v60, vcc
	v_cmp_le_i32_e32 vcc, v14, v152
	v_add_u32_e32 v14, 57, v0
	s_nop 0
	v_cndmask_b32_e32 v77, v198, v77, vcc
	v_cmp_le_i32_e32 vcc, v14, v152
	v_add_u32_e32 v14, 26, v0
	s_nop 0
	v_cndmask_b32_e32 v61, v198, v61, vcc
	v_cmp_le_i32_e32 vcc, v14, v152
	v_add_u32_e32 v14, 58, v0
	s_nop 0
	v_cndmask_b32_e32 v78, v198, v78, vcc
	v_cmp_le_i32_e32 vcc, v14, v152
	v_add_u32_e32 v14, 27, v0
	v_add_u32_e32 v0, 59, v0
	v_cndmask_b32_e32 v62, v198, v62, vcc
	v_cmp_le_i32_e32 vcc, v14, v152
	s_nop 1
	v_cndmask_b32_e32 v79, v198, v79, vcc
	v_cmp_le_i32_e32 vcc, v0, v152
	s_nop 1
	v_cndmask_b32_e32 v63, v198, v63, vcc
; template <int DK, int MODE> ...
;     ...
;   auto gload = [&](int jt) {
; #pragma unroll
;     for (int i = 0; i < NKL; ++i) {
;       const int id = tid + 256 * i, row = id / KCH, ch = id % KCH;
;       rk[i] = *(const u32x4*)(K + (size_t)(jt * 64 + row) * DK + ch * 8);
;     }
; #pragma unroll
;     for (int i = 0; i < 2; ++i) {
;       const int id = tid + 256 * i, row = id >> 3, ch = id & 7;
;       rv[i] = *(const u32x4*)(Vt + (size_t)row * Skv + jt * 64 + ch * 8);
;     }
;     if (MODE == 1) rf = F[jt * 64 + (tid & 63)];
;   };
;     ...
;         float mx = s0[0];
; #pragma unroll
;         for (int e = 1; e < 16; ++e) mx = fmaxf(mx, s0[e]);
; #pragma unroll
;         for (int e = 0; e < 16; ++e) mx = fmaxf(mx, s1[e]);
;         mx = fmaxf(mx, __shfl_xor(mx, 32));
;         if (__any(mx > m + 8.f)) {
;           const float mnew = fmaxf(m, mx);
;           const float alpha = __builtin_amdgcn_exp2f(m - mnew);
;           m = mnew; lsum *= alpha;
; #pragma unroll
;           for (int e = 0; e < 16; ++e) { o0[e] *= alpha; o1[e] *= alpha; }
;         }
.LBB0_529:
	s_nop 6
	v_max_f32_e32 v0, v64, v65
	v_max3_f32 v0, v0, v66, v67
	v_max3_f32 v0, v0, v68, v69
	v_max3_f32 v0, v0, v70, v71
	v_max3_f32 v0, v0, v72, v73
	v_max3_f32 v0, v0, v74, v75
	v_max3_f32 v0, v0, v76, v77
	v_max3_f32 v0, v0, v78, v79
	v_max3_f32 v0, v0, v48, v49
	v_max3_f32 v0, v0, v50, v51
	v_max3_f32 v0, v0, v52, v53
	v_max3_f32 v0, v0, v54, v55
	v_max3_f32 v0, v0, v56, v57
	v_max3_f32 v0, v0, v58, v59
	v_max3_f32 v0, v0, v60, v61
	v_max3_f32 v0, v0, v62, v63
	ds_bpermute_b32 v14, v216, v0
	s_waitcnt lgkmcnt(0)
	v_max_f32_e32 v0, v0, v14
	v_add_f32_e32 v14, 0x41000000, v155
	v_cmp_gt_f32_e32 vcc, v0, v14
	s_cbranch_vccz .LBB0_524
	v_max_f32_e32 v0, v0, v0
	v_max_f32_e32 v14, v155, v155
	v_max_f32_e32 v14, v14, v0
	v_sub_f32_e32 v0, v155, v14
	v_exp_f32_e32 v0, v0
	v_mov_b32_e32 v155, v14
	v_pk_mul_f32 v[30:31], v[30:31], v[0:1] op_sel_hi:[1,0]
	v_pk_mul_f32 v[28:29], v[28:29], v[0:1] op_sel_hi:[1,0]
	v_pk_mul_f32 v[26:27], v[26:27], v[0:1] op_sel_hi:[1,0]
	v_pk_mul_f32 v[24:25], v[24:25], v[0:1] op_sel_hi:[1,0]
	v_pk_mul_f32 v[22:23], v[22:23], v[0:1] op_sel_hi:[1,0]
	v_pk_mul_f32 v[20:21], v[20:21], v[0:1] op_sel_hi:[1,0]
	v_pk_mul_f32 v[18:19], v[18:19], v[0:1] op_sel_hi:[1,0]
	v_pk_mul_f32 v[16:17], v[16:17], v[0:1] op_sel_hi:[1,0]
	v_pk_mul_f32 v[46:47], v[46:47], v[0:1] op_sel_hi:[1,0]
	v_pk_mul_f32 v[44:45], v[44:45], v[0:1] op_sel_hi:[1,0]
	v_pk_mul_f32 v[42:43], v[42:43], v[0:1] op_sel_hi:[1,0]
	v_pk_mul_f32 v[40:41], v[40:41], v[0:1] op_sel_hi:[1,0]
	v_pk_mul_f32 v[38:39], v[38:39], v[0:1] op_sel_hi:[1,0]
	v_pk_mul_f32 v[36:37], v[36:37], v[0:1] op_sel_hi:[1,0]
	v_pk_mul_f32 v[34:35], v[34:35], v[0:1] op_sel_hi:[1,0]
	v_pk_mul_f32 v[32:33], v[32:33], v[0:1] op_sel_hi:[1,0]
	v_mul_f32_e32 v151, v151, v0
	s_branch .LBB0_524
.Lmla_inactive:
	global_load_dwordx4 v[88:91], v[170:171], off
	global_load_dwordx4 v[84:87], v[168:169], off
	global_load_dwordx4 v[10:13], v[166:167], off
	global_load_dwordx4 v[6:9], v[164:165], off
	s_nop 0
	global_load_dwordx4 v[2:5], v[162:163], off
	s_branch .LBB0_525
